# v40 + SwiGLU GEMM tile order: 4 row panels x 8 column tiles per XCD step (was 8 x 4): beyond-L2 traffic shifts from activations to the cache-resident weights
# speedup vs baseline: 1.0033x; 1.0033x over previous
;     __host__ __device__ bool next(int i, Unit& u) const { const bool ok = StaticOrder::next(i, u); u.lm = 0; u.ln = 0; return ok; }
;     __host__ __device__ bool next(int i, Unit& u) const {
;         if ((long)i * G + c >= nwg) return false;
;         const long L = rev ? (long)((nwg - 1 - c) / G - i) * G + c : (long)i * G + c;
;         int wgid = (int)L; { const int q = nwg / NXCD, r = nwg % NXCD, xcd = wgid % NXCD, off = wgid / NXCD; wgid = (xcd < r ? xcd * (q + 1) : r * (q + 1) + (xcd - r) * q) + off; }
;         const int nig = wgm * nN, gid = wgid / nig, fm = gid * wgm, gsz = (nM - fm) < wgm ? (nM - fm) : wgm;
;         u.pm = fm + ((wgid % nig) % gsz); u.pn = (wgid % nig) / gsz; u.lm = fixed ? 0 : u.pm; u.ln = fixed ? 0 : u.pn; return true;
; template <class Epi, class Sched, bool ALIGN_EPI = false, bool SP2 = false>
; __device__ __forceinline__ void gemm_phase(PG8_LAS unsigned char* lds, const Gemm g, const Sched& S, const Epi& E, const int wave_id) {
;     ...
;     for (int i = 0; i < 2; ++i) { int R, C; stage_rc(tid * 16 + i * 8192, R, C); const int Rb = Epi::PERM ? ((R & ~31) + perm32(R & 31)) : R;
;         voffA[i] = (unsigned)(R * K + C) * 2u; voffB[i] = (unsigned)(Rb * K + C) * 2u; }
;     const size_t kstep = (size_t)(BK * 2);
;     const size_t hstep = (size_t)HALF * K * 2;
;     const size_t tstep = 2 * hstep;
;     const unsigned ldsw = (unsigned)wid * 1024u;
;     const int aoff = lds_byte(wr * 64 + fr, fq * 8), boff = lds_byte(wc * 32 + fr, fq * 8);
;     ...
;     Unit cur, nxt; int ui = 0, tp = 0;
;     if (!S.next(0, cur)) return;
;     f32x4 acc[2][2][4][2];
; #pragma unroll
;     for (int a = 0; a < 2; ++a)
; #pragma unroll
;         for (int b = 0; b < 2; ++b)
; #pragma unroll
;             for (int m = 0; m < 4; ++m)
; #pragma unroll
;                 for (int n = 0; n < 2; ++n) acc[a][b][m][n] = (f32x4){0.f, 0.f, 0.f, 0.f};
;     bf16x8 At[4][2], B0[2][2], B1[2][2];
;     const char* cA = (const char*)g.A + (size_t)cur.lm * tstep; const char* cB = (const char*)g.Bt + (size_t)cur.ln * tstep;
;     if constexpr (Epi::HAS_PREP) E.prep(cur, 0, lds, tid);
;     S.a_ready(cur);
;     if constexpr (SP2) {
;         PG8_STAGE(PG8_SB(0, 0), cB, voffB); PG8_STAGE(PG8_SB(0, 1), cB + hstep, voffB); PG8_STAGE(PG8_SA(0, 0), cA, voffA); PG8_STAGE(PG8_SA(0, 1), cA + hstep, voffA);
;         if (wr == 1) PG8_BAR;
;         PG8_WAIT_V(2); PG8_BAR;
.LBB0_629:
	s_andn2_b64 vcc, exec, s[2:3]
	s_cbranch_vccnz .LBB0_733
	v_readlane_b32 s2, v253, 50
	v_readlane_b32 s12, v254, 63
	v_readlane_b32 s3, v253, 51
	v_readlane_b32 s13, v252, 0
	v_readlane_b32 s14, v252, 1
	v_readlane_b32 s15, v252, 2
	s_mov_b32 s4, s2
	s_mov_b64 s[2:3], s[12:13]
	v_readlane_b32 s11, v253, 0
	s_mov_b64 s[8:9], s[14:15]
	s_ashr_i32 s26, s4, 3
	s_cmpk_gt_i32 s26, 0x15ff
	v_mbcnt_lo_u32_b32 v10, -1, 0
	v_mbcnt_hi_u32_b32 v10, -1, v10
	s_cbranch_scc1 .LBB0_653
	s_add_u32 s2, s8, 0x600000
	s_addc_u32 s3, s9, 0
	s_lshr_b32 s4, s26, 29
	s_add_i32 s4, s26, s4
	s_ashr_i32 s5, s4, 3
	s_and_b32 s4, s4, -8
	s_sub_i32 s4, s26, s4
	s_cmp_lt_i32 s4, 0
	s_movk_i32 s10, 0x2c1
	s_cselect_b32 s10, s10, 0x2c0
	s_mul_i32 s4, s4, s10
	s_add_i32 s4, s4, s5
	s_mul_hi_i32 s5, s4, 0x2e8ba2e9
	s_lshr_b32 s10, s5, 31
	s_ashr_i32 s5, s5, 5
	s_add_i32 s5, s5, s10
	s_lshl_b32 s12, s5, 2
	s_mulk_i32 s5, 0xb0
	s_sub_i32 s10, s4, s5
	s_bfe_u32 s4, s10, 0x3001c
	s_add_i32 s4, s10, s4
	s_and_b32 s4, s4, 0xfffc
	s_sub_i32 s4, s10, s4
	s_sext_i32_i16 s4, s4
	v_lshl_add_u32 v1, s11, 6, v10
	s_add_i32 s40, s12, s4
	s_movk_i32 s4, 0x100
	v_cmp_gt_i32_e64 s[36:37], s4, v1
	v_ashrrev_i32_e32 v3, 31, v1
	v_lshrrev_b32_e32 v3, 26, v3
	v_add_u32_e32 v3, v1, v3
	v_ashrrev_i32_e32 v11, 6, v3
	v_bfe_i32 v3, v1, 27, 1
	v_lshlrev_b32_e32 v2, 4, v1
	v_lshrrev_b32_e32 v3, 22, v3
	v_add_u32_e32 v3, v2, v3
	v_and_b32_e32 v3, 0xfffffc00, v3
	v_sub_u32_e32 v3, v2, v3
	v_lshrrev_b32_e32 v4, 4, v3
	v_bitop3_b32 v3, v4, v3, 32 bitop3:0x6c
	v_ashrrev_i32_e32 v5, 31, v3
	v_lshrrev_b32_e32 v5, 26, v5
	v_add_u32_e32 v5, v3, v5
	v_readlane_b32 s12, v252, 15
	v_lshlrev_b32_e32 v4, 3, v11
	v_ashrrev_i32_e32 v12, 6, v5
	v_and_b32_e32 v5, 0xc0, v5
	s_ashr_i32 s46, s26, 31
	s_mul_i32 s4, s12, 0x6300000
	v_and_b32_e32 v4, -16, v4
	v_sub_u32_e32 v3, v3, v5
	s_add_u32 s4, s8, s4
	v_add_u32_e32 v4, v12, v4
	v_ashrrev_i16_sdwa v3, v223, sext(v3) dst_sel:DWORD dst_unused:UNUSED_PAD src0_sel:DWORD src1_sel:BYTE_0
	s_addc_u32 s5, s9, 0
	v_lshlrev_b32_e32 v6, 5, v11
	v_bfe_i32 v13, v3, 0, 16
	v_lshlrev_b32_e32 v3, 1, v4
	v_lshrrev_b32_e32 v5, 2, v4
	v_and_b32_e32 v7, 3, v12
	s_mov_b32 s38, 0xfffe0
	s_bitcmp0_b32 s12, 0
	s_mov_b32 s12, 0x1dc00000
	v_and_b32_e32 v6, 32, v6
	v_and_b32_e32 v3, 24, v3
	v_and_b32_e32 v5, 4, v5
	v_and_or_b32 v7, v4, s38, v7
	s_cselect_b32 s12, s12, 0x25c00000
	v_or3_b32 v3, v7, v5, v3
	v_add_lshl_u32 v5, v6, v13, 1
	v_add_u32_e32 v2, 0x2000, v2
	s_add_u32 s47, s8, s12
	v_lshl_add_u32 v132, v3, 12, v5
	v_ashrrev_i32_e32 v3, 31, v2
	s_addc_u32 s48, s9, 0
	v_lshrrev_b32_e32 v3, 22, v3
	s_add_u32 s49, s4, 0x2800000
	s_sext_i32_i16 s4, s10
	v_add_u32_e32 v3, v2, v3
	s_addc_u32 s52, s5, 0
	s_bfe_u32 s4, s4, 0x3001c
	v_ashrrev_i32_e32 v14, 10, v3
	s_add_i32 s10, s10, s4
	v_mul_i32_i24_e32 v3, 0x400, v14
	s_sext_i32_i16 s4, s10
	v_sub_u32_e32 v2, v2, v3
	s_lshr_b32 s10, s4, 2
	v_lshrrev_b32_e32 v3, 4, v2
	v_readlane_b32 s13, v252, 16
	s_bfe_i64 s[4:5], s[10:11], 0x100000
	s_ashr_i32 s41, s40, 31
	v_bitop3_b32 v2, v3, v2, 32 bitop3:0x6c
	s_lshl_b64 s[4:5], s[4:5], 20
	s_lshl_b64 s[12:13], s[40:41], 20
	v_lshl_add_u32 v130, v4, 12, v5
	v_ashrrev_i32_e32 v4, 31, v2
	s_add_u32 s20, s47, s12
	v_lshrrev_b32_e32 v4, 26, v4
	s_addc_u32 s21, s48, s13
	v_add_u32_e32 v4, v2, v4
	s_add_u32 s42, s49, s4
	v_lshlrev_b32_e32 v3, 3, v14
	v_ashrrev_i32_e32 v15, 6, v4
	v_and_b32_e32 v4, 0xc0, v4
	s_addc_u32 s43, s52, s5
	s_ashr_i32 s14, s11, 2
	s_lshl_b32 s41, s11, 10
	v_and_b32_e32 v3, -16, v3
	v_sub_u32_e32 v2, v2, v4
	s_cmp_eq_u32 s14, 1
	v_add_u32_e32 v3, v15, v3
	v_ashrrev_i16_sdwa v2, v223, sext(v2) dst_sel:DWORD dst_unused:UNUSED_PAD src0_sel:DWORD src1_sel:BYTE_0
	s_cselect_b64 s[4:5], -1, 0
	s_add_i32 s53, s41, 0
	v_lshlrev_b32_e32 v5, 5, v14
	v_bfe_i32 v16, v2, 0, 16
	v_lshlrev_b32_e32 v2, 1, v3
	v_lshrrev_b32_e32 v4, 2, v3
	v_and_b32_e32 v6, 3, v15
	s_add_i32 m0, s53, 0x10000
	s_add_i32 s15, s53, 0x12000
	v_and_b32_e32 v5, 32, v5
	v_and_b32_e32 v2, 24, v2
	v_and_b32_e32 v4, 4, v4
	v_and_or_b32 v6, v3, s38, v6
	s_add_u32 s16, s42, 0x80000
	v_or3_b32 v2, v6, v4, v2
	v_add_lshl_u32 v4, v5, v16, 1
	s_waitcnt lgkmcnt(0)
	s_addc_u32 s17, s43, 0
	s_add_i32 s18, s53, 0x14000
	v_lshl_add_u32 v136, v2, 12, v4
	global_load_lds_dwordx4 v132, s[42:43]
	s_mov_b32 m0, s15
	s_add_i32 s19, s53, 0x16000
	global_load_lds_dwordx4 v136, s[42:43]
	s_mov_b32 m0, s18
	s_add_i32 s56, s53, 0x2000
	global_load_lds_dwordx4 v132, s[16:17]
	s_mov_b32 m0, s19
	s_add_u32 s12, s20, 0x80000
	global_load_lds_dwordx4 v136, s[16:17]
	s_mov_b32 m0, s53
	s_addc_u32 s13, s21, 0
	s_add_i32 s57, s53, 0x4000
	v_lshl_add_u32 v134, v3, 12, v4
	global_load_lds_dwordx4 v130, s[20:21]
	s_mov_b32 m0, s56
	s_add_i32 s64, s53, 0x6000
	global_load_lds_dwordx4 v134, s[20:21]
	s_mov_b32 m0, s57
	v_mov_b32_e32 v133, v0
	global_load_lds_dwordx4 v130, s[12:13]
	s_mov_b32 m0, s64
	v_mov_b32_e32 v137, v0
	global_load_lds_dwordx4 v134, s[12:13]
	v_mov_b32_e32 v131, v0
	v_mov_b32_e32 v135, v0
	s_and_saveexec_b64 vcc, s[36:37]
	s_cbranch_execz .Lprep_1
	v_lshl_add_u32 v90, s40, 8, v1
	v_ashrrev_i32_e32 v91, 31, v90
	v_lshlrev_b64 v[90:91], 7, v[90:91]
	v_lshl_add_u64 v[108:109], s[2:3], 0, v[90:91]
	global_load_dwordx4 v[90:93], v[108:109], off offset:48
	global_load_dwordx4 v[94:97], v[108:109], off offset:32
	global_load_dwordx4 v[100:103], v[108:109], off
	global_load_dwordx4 v[104:107], v[108:109], off offset:16
	global_load_dwordx4 v[114:117], v[108:109], off offset:112
	global_load_dwordx4 v[118:121], v[108:109], off offset:96
	global_load_dwordx4 v[122:125], v[108:109], off offset:80
	global_load_dwordx4 v[126:129], v[108:109], off offset:64
	s_waitcnt vmcnt(4)
	v_pk_add_f32 v[102:103], v[102:103], v[106:107]
	v_pk_add_f32 v[100:101], v[100:101], v[104:105]
	v_pk_add_f32 v[96:97], v[102:103], v[96:97]
	v_pk_add_f32 v[94:95], v[100:101], v[94:95]
	v_pk_add_f32 v[110:111], v[96:97], v[92:93]
	v_pk_add_f32 v[112:113], v[94:95], v[90:91]
	s_waitcnt vmcnt(0)
	v_pk_add_f32 v[128:129], v[110:111], v[128:129]
	v_pk_add_f32 v[126:127], v[112:113], v[126:127]
	v_pk_add_f32 v[124:125], v[128:129], v[124:125]
	v_pk_add_f32 v[122:123], v[126:127], v[122:123]
	v_pk_add_f32 v[120:121], v[124:125], v[120:121]
	v_pk_add_f32 v[118:119], v[122:123], v[118:119]
	v_pk_add_f32 v[116:117], v[120:121], v[116:117]
	v_pk_add_f32 v[114:115], v[118:119], v[114:115]
	s_nop 0
	v_pk_mov_b32 v[118:119], v[114:115], v[116:117] op_sel:[1,0]
	v_mov_b32_e32 v115, v117
	v_pk_add_f32 v[114:115], v[118:119], v[114:115]
	s_nop 0
	v_add_f32_e32 v114, v114, v115
	v_fmamk_f32 v114, v114, 0x3a000000, v221
	v_rsq_f32_e32 v114, v114
	v_lshl_add_u32 v115, v1, 2, 0
	v_add_u32_e32 v115, 0x20000, v115
	ds_write_b32 v115, v114

;     __host__ __device__ bool next(int i, Unit& u) const { const bool ok = StaticOrder::next(i, u); u.lm = 0; u.ln = 0; return ok; }
;     __host__ __device__ bool next(int i, Unit& u) const {
;         if ((long)i * G + c >= nwg) return false;
;         const long L = rev ? (long)((nwg - 1 - c) / G - i) * G + c : (long)i * G + c;
;         int wgid = (int)L; { const int q = nwg / NXCD, r = nwg % NXCD, xcd = wgid % NXCD, off = wgid / NXCD; wgid = (xcd < r ? xcd * (q + 1) : r * (q + 1) + (xcd - r) * q) + off; }
;         const int nig = wgm * nN, gid = wgid / nig, fm = gid * wgm, gsz = (nM - fm) < wgm ? (nM - fm) : wgm;
;         u.pm = fm + ((wgid % nig) % gsz); u.pn = (wgid % nig) / gsz; u.lm = fixed ? 0 : u.pm; u.ln = fixed ? 0 : u.pn; return true;
.LBB0_638:
	s_add_i32 s69, s69, 1
	s_mul_i32 s13, s69, s87
	s_mul_hi_u32 s15, s69, s86
	s_add_i32 s15, s15, s13
	s_mul_i32 s13, s69, s86
	s_add_u32 s16, s13, s26
	s_addc_u32 s17, s15, s46
	v_cmp_gt_i64_e32 vcc, s[16:17], v[204:205]
	v_cmp_lt_i64_e64 s[38:39], s[16:17], v[202:203]
	s_cbranch_vccnz .LBB0_640
	s_ashr_i32 s12, s16, 31
	s_lshr_b32 s12, s12, 29
	s_add_i32 s12, s16, s12
	s_ashr_i32 s13, s12, 3
	s_and_b32 s12, s12, -8
	s_sub_i32 s12, s16, s12
	s_cmp_lt_i32 s12, 0
	s_movk_i32 s14, 0x2c1
	s_cselect_b32 s14, s14, 0x2c0
	s_mul_i32 s12, s12, s14
	s_add_i32 s12, s12, s13
	s_mul_hi_i32 s13, s12, 0x2e8ba2e9
	s_lshr_b32 s14, s13, 31
	s_ashr_i32 s13, s13, 5
	s_add_i32 s13, s13, s14
	s_lshl_b32 s14, s13, 2
	s_sub_i32 s15, 0x80, s14
	s_min_i32 s15, s15, 4
	s_abs_i32 s16, s15
	v_cvt_f32_u32_e32 v2, s16
	s_sub_i32 s18, 0, s16
	s_mulk_i32 s13, 0xb0
	s_sub_i32 s13, s12, s13
	v_rcp_iflag_f32_e32 v2, v2
	s_abs_i32 s12, s13
	s_xor_b32 s17, s13, s15
	s_ashr_i32 s17, s17, 31
	v_mul_f32_e32 v2, 0x4f7ffffe, v2
	v_cvt_u32_f32_e32 v2, v2
	s_nop 0
	v_readfirstlane_b32 s19, v2
	s_mul_i32 s18, s18, s19
	s_mul_hi_u32 s18, s19, s18
	s_add_i32 s19, s19, s18
	s_mul_hi_u32 s18, s12, s19
	s_mul_i32 s19, s18, s16
	s_sub_i32 s12, s12, s19
	s_add_i32 s44, s18, 1
	s_sub_i32 s19, s12, s16
	s_cmp_ge_u32 s12, s16
	s_cselect_b32 s18, s44, s18
	s_cselect_b32 s12, s19, s12
	s_add_i32 s19, s18, 1
	s_cmp_ge_u32 s12, s16
	s_cselect_b32 s12, s19, s18
	s_xor_b32 s12, s12, s17
	s_sub_i32 s12, s12, s17
	s_mul_i32 s15, s12, s15
	s_sub_i32 s13, s13, s15
	s_add_i32 s14, s14, s13
